# P3 scan: the 4 dv-slice chains of one (mixer,b,h) placed on one XCD (shared QB/KT/PN chunk operands hit that L2)
# speedup vs baseline: 1.0244x; 1.0043x over previous
; __device__ __forceinline__ void seq_item(const Params& p, int item, char* smem, const bool write_o = true) {
;   const int tid = threadIdx.x, lane = tid & 63, w = tid >> 6;
;   const int m = 1 - (item >> 7); const int rem = item & 127; const int bh = rem >> 2, sl = rem & 3; const int b = bh >> 2, h = bh & 3;
;   char* ws = p.ws;
;   u16* STs = (u16*)smem;
;   u16* VTs = (u16*)(smem + 8704);
;   const int r = lane & 31, hh = (lane >> 5) * 8;
;   const int dcol = w * 32 + r;
;   u16* Om = (u16*)(ws + OFF_O) + (size_t)m * NT * 512;
;   float* SSQO = (float*)(ws + OFF_SSQO) + (size_t)m * NT * 16;
;   const float* DVEC = (const float*)(ws + OFF_DVEC);
;   f32x16 S = zero16();
;   __syncthreads();
;   uint4 vt4; bf16x8 ktf[4], pnf[8], qbf[8]; float dvn; u16 o0[16];
; __device__ __forceinline__ void phase3(const Params& p, char* smem, const bool write_o = true) {
;   for (int it = blockIdx.x; it < 256; it += gridDim.x) seq_item(p, it, smem, write_o);
.LBB0_1010:
	s_or_b64 exec, exec, s[0:1]
	s_ashr_i32 s33, s82, 31
	s_cmpk_gt_i32 s96, 0xff
	s_waitcnt lgkmcnt(0)
	s_barrier
	s_cbranch_scc1 .LBB0_1062
	v_accvgpr_read_b32 v1, a128
	v_and_b32_e32 v2, 31, v237
	v_and_b32_e32 v3, 0x1e0, v1
	s_movk_i32 s0, 0x80
	v_bfe_u32 v0, v237, 5, 1
	v_or_b32_e32 v5, v3, v2
	v_and_b32_e32 v4, 56, v234
	v_cmp_gt_u32_e64 s[4:5], s0, v237
	s_movk_i32 s0, 0x7f
	v_mov_b32_e32 v1, 0
	v_cmp_lt_u32_e64 s[6:7], s0, v237
	v_accvgpr_read_b32 v7, a131
	v_lshlrev_b32_e32 v6, 1, v4
	s_movk_i32 s0, 0x90
	v_lshlrev_b32_e32 v8, 4, v0
	v_lshlrev_b32_e32 v10, 2, v0
	v_lshlrev_b32_e32 v0, 2, v5
	v_mad_u32_u24 v59, v7, s0, v6
	v_mad_u32_u24 v80, v2, s0, v8
	v_lshl_add_u64 v[12:13], s[80:81], 0, v[0:1]
	s_mov_b64 s[0:1], 0x3884000
	v_lshlrev_b32_e32 v0, 7, v5
	v_lshl_add_u64 v[36:37], v[12:13], 0, s[0:1]
	v_lshl_add_u64 v[12:13], s[80:81], 0, v[0:1]
	v_mov_b32_e32 v9, v1
	v_lshl_add_u64 v[12:13], v[12:13], 0, v[8:9]
	s_mov_b64 s[0:1], 0xcf35000
	v_lshlrev_b32_e32 v0, 8, v5
	s_add_u32 s26, s80, 0x8e35000
	v_lshl_add_u64 v[38:39], v[12:13], 0, s[0:1]
	v_lshl_add_u64 v[12:13], s[80:81], 0, v[0:1]
	v_lshlrev_b32_e32 v0, 1, v2
	v_and_b32_e32 v11, 4, v7
	s_addc_u32 s27, s81, 0
	v_lshl_add_u64 v[46:47], s[80:81], 0, v[0:1]
	v_accvgpr_read_b32 v0, a129
	s_add_u32 s10, s80, 0xef35000
	v_or_b32_e32 v81, v11, v3
	v_lshlrev_b32_e32 v0, 13, v0
	v_lshlrev_b32_e32 v3, 8, v2
	s_addc_u32 s11, s81, 0
	v_lshl_add_u64 v[12:13], v[12:13], 0, v[8:9]
	s_mov_b64 s[0:1], 0x10f35000
	v_mov_b32_e32 v7, v1
	v_or3_b32 v0, v0, v3, v8
	s_add_u32 s28, s80, 0x3984000
	v_lshl_add_u64 v[40:41], v[12:13], 0, s[0:1]
	s_mov_b64 s[0:1], 0xaf35000
	v_lshl_add_u64 v[44:45], s[10:11], 0, v[6:7]
	v_lshl_add_u64 v[6:7], s[80:81], 0, v[0:1]
	v_mbcnt_lo_u32_b32 v0, -1, 0
	s_addc_u32 s29, s81, 0
	v_lshl_add_u64 v[42:43], v[12:13], 0, s[0:1]
	s_mov_b64 s[0:1], 0x8e45000
	v_mbcnt_hi_u32_b32 v84, -1, v0
	v_lshlrev_b32_e32 v14, 1, v5
	v_mul_u32_u24_e32 v15, 0x110, v2
	v_mul_u32_u24_e32 v16, 0x110, v11
	s_add_u32 s30, s80, 0x3984400
	v_lshl_add_u64 v[48:49], v[46:47], 0, s[0:1]
	s_mov_b64 s[0:1], 0x10f3d080
	v_and_b32_e32 v0, 64, v84
	s_mov_b32 s3, 0
	v_cmp_eq_u32_e64 s[8:9], 0, v2
	v_lshlrev_b32_e32 v34, 9, v5
	v_mov_b32_e32 v35, v1
	s_addc_u32 s31, s81, 0
	v_lshl_add_u64 v[50:51], v[6:7], 0, s[0:1]
	v_lshlrev_b32_e32 v52, 1, v4
	v_mov_b32_e32 v53, v1
	s_movk_i32 s34, 0x2000
	v_lshlrev_b32_e32 v54, 1, v2
	v_mov_b32_e32 v55, v1
	v_add_u32_e32 v82, v14, v16
	v_add_u32_e32 v83, v8, v15
	v_xor_b32_e32 v85, 16, v84
	v_add_u32_e32 v86, 64, v0
	s_mov_b32 s35, 0x8e35000
	s_mov_b64 s[12:13], 0x1000
	s_mov_b64 s[14:15], 0x8000
	s_mov_b32 s36, 0x4200000
	v_lshlrev_b32_e32 v56, 2, v10
	s_and_b32 s44, s96, 0x80
	s_lshr_b32 s0, s96, 5
	s_and_b32 s0, s0, 3
	s_lshl_b32 s0, s0, 5
	s_or_b32 s44, s44, s0
	s_and_b32 s0, s96, 7
	s_lshl_b32 s0, s0, 2
	s_or_b32 s44, s44, s0
	s_lshr_b32 s0, s96, 3
	s_and_b32 s0, s0, 3
	s_or_b32 s44, s44, s0
	s_cmpk_ge_u32 s82, 0x100
	s_cselect_b32 s44, s44, s96
	s_mov_b32 s37, s44
	s_branch .LBB0_1013
